# GEMM main loop: all stage waits as late as possible, vmcnt(10) before opening barriers of phases 1,2,4
# baseline (speedup 1.0000x reference)
.LBB0_894:
	s_add_i32 s6, s2, 2
	s_add_u32 s7, s64, s0
	s_addc_u32 s3, s65, s1
	s_add_u32 s8, s66, s0
	s_addc_u32 s9, s67, s1
	s_add_i32 s33, 0, 0x10000
	v_add_u32_e32 v160, s33, v165
	ds_read_b128 v[148:151], v160
	ds_read_b128 v[152:155], v160 offset:1024
	ds_read_b128 v[156:159], v160 offset:2048
	ds_read_b128 v[160:163], v160 offset:3072
	s_cmp_eq_u32 s92, s2
	s_cselect_b32 s2, s72, s7
	s_cselect_b32 s3, s73, s3
	s_cselect_b32 s9, s75, s9
	s_cselect_b32 s8, s74, s8
	v_lshl_add_u64 v[232:233], s[64:65], 0, v[132:133]
	s_add_i32 m0, s84, 0xc000
	ds_read_b128 v[196:199], v195
	ds_read_b128 v[200:203], v195 offset:1024
	ds_read_b128 v[204:207], v195 offset:2048
	ds_read_b128 v[208:211], v195 offset:3072
	ds_read_b128 v[212:215], v195 offset:4096
	ds_read_b128 v[216:219], v195 offset:5120
	ds_read_b128 v[220:223], v195 offset:6144
	ds_read_b128 v[224:227], v195 offset:7168
	global_load_lds_dwordx4 v[232:233], off
	v_lshl_add_u64 v[232:233], s[64:65], 0, v[134:135]
	s_add_i32 m0, s84, 0xe000
	s_nop 0
	global_load_lds_dwordx4 v[232:233], off
	s_waitcnt lgkmcnt(8)
	s_waitcnt vmcnt(10)
	s_barrier
	s_waitcnt lgkmcnt(0)
	s_setprio 1
	s_waitcnt lgkmcnt(0)
	v_mfma_f32_16x16x32_bf16 v[128:131], v[148:151], v[196:199], v[128:131]
	v_mfma_f32_16x16x32_bf16 v[124:127], v[156:159], v[196:199], v[124:127]
	v_mfma_f32_16x16x32_bf16 v[108:111], v[148:151], v[204:207], v[108:111]
	v_mfma_f32_16x16x32_bf16 v[100:103], v[156:159], v[204:207], v[100:103]
	v_mfma_f32_16x16x32_bf16 v[88:91], v[148:151], v[212:215], v[88:91]
	v_mfma_f32_16x16x32_bf16 v[84:87], v[156:159], v[212:215], v[84:87]
	v_mfma_f32_16x16x32_bf16 v[56:59], v[148:151], v[220:223], v[56:59]
	v_mfma_f32_16x16x32_bf16 v[44:47], v[156:159], v[220:223], v[44:47]
	v_mfma_f32_16x16x32_bf16 v[128:131], v[152:155], v[200:203], v[128:131]
	v_mfma_f32_16x16x32_bf16 v[124:127], v[160:163], v[200:203], v[124:127]
	v_mfma_f32_16x16x32_bf16 v[108:111], v[152:155], v[208:211], v[108:111]
	v_mfma_f32_16x16x32_bf16 v[100:103], v[160:163], v[208:211], v[100:103]
	v_mfma_f32_16x16x32_bf16 v[88:91], v[152:155], v[216:219], v[88:91]
	v_mfma_f32_16x16x32_bf16 v[84:87], v[160:163], v[216:219], v[84:87]
	v_mfma_f32_16x16x32_bf16 v[56:59], v[152:155], v[224:227], v[56:59]
	v_mfma_f32_16x16x32_bf16 v[44:47], v[160:163], v[224:227], v[44:47]
	s_setprio 0
	s_barrier
	s_add_i32 s7, 0, 0x14000
	s_add_i32 s33, s33, s87
	v_lshl_add_u64 v[248:249], s[8:9], 0, v[138:139]
	s_add_u32 s8, s8, s34
	v_add_u32_e32 v244, s7, v165
	s_mov_b32 m0, s33
	s_addc_u32 s9, s9, s35
	ds_read_b128 v[232:235], v244
	ds_read_b128 v[236:239], v244 offset:1024
	ds_read_b128 v[240:243], v244 offset:2048
	ds_read_b128 v[244:247], v244 offset:3072
	global_load_lds_dwordx4 v[248:249], off
	v_lshl_add_u64 v[250:251], s[8:9], 0, v[138:139]
	s_add_i32 m0, s33, 0x2000
	s_nop 0
	global_load_lds_dwordx4 v[250:251], off
	s_waitcnt vmcnt(10)
	s_barrier
	s_waitcnt lgkmcnt(0)
	s_setprio 1
	s_waitcnt lgkmcnt(0)
	v_mfma_f32_16x16x32_bf16 v[120:123], v[232:235], v[196:199], v[120:123]
	v_mfma_f32_16x16x32_bf16 v[116:119], v[240:243], v[196:199], v[116:119]
	v_mfma_f32_16x16x32_bf16 v[112:115], v[232:235], v[204:207], v[112:115]
	v_mfma_f32_16x16x32_bf16 v[104:107], v[240:243], v[204:207], v[104:107]
	v_mfma_f32_16x16x32_bf16 v[96:99], v[232:235], v[212:215], v[96:99]
	v_mfma_f32_16x16x32_bf16 v[92:95], v[240:243], v[212:215], v[92:95]
	v_mfma_f32_16x16x32_bf16 v[80:83], v[232:235], v[220:223], v[80:83]
	v_mfma_f32_16x16x32_bf16 v[76:79], v[240:243], v[220:223], v[76:79]
	v_mfma_f32_16x16x32_bf16 v[120:123], v[236:239], v[200:203], v[120:123]
	v_mfma_f32_16x16x32_bf16 v[116:119], v[244:247], v[200:203], v[116:119]
	v_mfma_f32_16x16x32_bf16 v[112:115], v[236:239], v[208:211], v[112:115]
	v_mfma_f32_16x16x32_bf16 v[104:107], v[244:247], v[208:211], v[104:107]
	v_mfma_f32_16x16x32_bf16 v[96:99], v[236:239], v[216:219], v[96:99]
	v_mfma_f32_16x16x32_bf16 v[92:95], v[244:247], v[216:219], v[92:95]
	v_mfma_f32_16x16x32_bf16 v[80:83], v[236:239], v[224:227], v[80:83]
	v_mfma_f32_16x16x32_bf16 v[76:79], v[244:247], v[224:227], v[76:79]
	s_setprio 0
	s_add_u32 s76, s2, s30
	s_mov_b32 m0, s84
	v_lshl_add_u64 v[250:251], s[2:3], 0, v[140:141]
	s_addc_u32 s77, s3, s31
	s_barrier
	ds_read_b128 v[196:199], v195 offset:16384
	ds_read_b128 v[200:203], v195 offset:17408
	ds_read_b128 v[204:207], v195 offset:18432
	ds_read_b128 v[208:211], v195 offset:19456
	ds_read_b128 v[212:215], v195 offset:20480
	ds_read_b128 v[216:219], v195 offset:21504
	ds_read_b128 v[220:223], v195 offset:22528
	ds_read_b128 v[224:227], v195 offset:23552
	global_load_lds_dwordx4 v[250:251], off
	v_lshl_add_u64 v[252:253], s[76:77], 0, v[140:141]
	s_mov_b32 m0, s93
	s_nop 0
	global_load_lds_dwordx4 v[252:253], off
	s_barrier
	s_waitcnt lgkmcnt(0)
	s_setprio 1
	s_waitcnt lgkmcnt(0)
	v_mfma_f32_16x16x32_bf16 v[64:67], v[148:151], v[196:199], v[64:67]
	v_mfma_f32_16x16x32_bf16 v[60:63], v[156:159], v[196:199], v[60:63]
	v_mfma_f32_16x16x32_bf16 v[40:43], v[148:151], v[204:207], v[40:43]
	v_mfma_f32_16x16x32_bf16 v[36:39], v[156:159], v[204:207], v[36:39]
	v_mfma_f32_16x16x32_bf16 v[22:25], v[148:151], v[212:215], v[22:25]
	v_mfma_f32_16x16x32_bf16 v[18:21], v[156:159], v[212:215], v[18:21]
	v_mfma_f32_16x16x32_bf16 v[6:9], v[148:151], v[220:223], v[6:9]
	v_mfma_f32_16x16x32_bf16 v[2:5], v[156:159], v[220:223], v[2:5]
	v_mfma_f32_16x16x32_bf16 v[64:67], v[152:155], v[200:203], v[64:67]
	v_mfma_f32_16x16x32_bf16 v[60:63], v[160:163], v[200:203], v[60:63]
	v_mfma_f32_16x16x32_bf16 v[40:43], v[152:155], v[208:211], v[40:43]
	v_mfma_f32_16x16x32_bf16 v[36:39], v[160:163], v[208:211], v[36:39]
	v_mfma_f32_16x16x32_bf16 v[22:25], v[152:155], v[216:219], v[22:25]
	v_mfma_f32_16x16x32_bf16 v[18:21], v[160:163], v[216:219], v[18:21]
	v_mfma_f32_16x16x32_bf16 v[6:9], v[152:155], v[224:227], v[6:9]
	v_mfma_f32_16x16x32_bf16 v[2:5], v[160:163], v[224:227], v[2:5]
	s_setprio 0
	s_barrier
	s_add_u32 s2, s8, s34
	s_addc_u32 s3, s9, s35
	s_add_i32 s7, s7, s87
	s_add_u32 s8, s2, s34
	v_lshl_add_u64 v[148:149], s[2:3], 0, v[138:139]
	s_mov_b32 m0, s7
	s_addc_u32 s9, s3, s35
	global_load_lds_dwordx4 v[148:149], off
	v_lshl_add_u64 v[252:253], s[8:9], 0, v[138:139]
	s_add_i32 m0, s7, 0x2000
	s_nop 0
	global_load_lds_dwordx4 v[252:253], off
	s_waitcnt vmcnt(10)
	s_barrier
	s_setprio 1
	v_mfma_f32_16x16x32_bf16 v[72:75], v[232:235], v[196:199], v[72:75]
	v_mfma_f32_16x16x32_bf16 v[68:71], v[240:243], v[196:199], v[68:71]
	v_mfma_f32_16x16x32_bf16 v[52:55], v[232:235], v[204:207], v[52:55]
	v_mfma_f32_16x16x32_bf16 v[48:51], v[240:243], v[204:207], v[48:51]
	v_mfma_f32_16x16x32_bf16 v[32:35], v[232:235], v[212:215], v[32:35]
	v_mfma_f32_16x16x32_bf16 v[28:31], v[240:243], v[212:215], v[28:31]
	v_mfma_f32_16x16x32_bf16 v[14:17], v[232:235], v[220:223], v[14:17]
	v_mfma_f32_16x16x32_bf16 v[10:13], v[240:243], v[220:223], v[10:13]
	v_mfma_f32_16x16x32_bf16 v[72:75], v[236:239], v[200:203], v[72:75]
	v_mfma_f32_16x16x32_bf16 v[68:71], v[244:247], v[200:203], v[68:71]
	v_mfma_f32_16x16x32_bf16 v[52:55], v[236:239], v[208:211], v[52:55]
	v_mfma_f32_16x16x32_bf16 v[48:51], v[244:247], v[208:211], v[48:51]
	v_mfma_f32_16x16x32_bf16 v[32:35], v[236:239], v[216:219], v[32:35]
	v_mfma_f32_16x16x32_bf16 v[28:31], v[244:247], v[216:219], v[28:31]
	v_mfma_f32_16x16x32_bf16 v[14:17], v[236:239], v[224:227], v[14:17]
	v_mfma_f32_16x16x32_bf16 v[10:13], v[244:247], v[224:227], v[10:13]
	s_setprio 0
	s_add_i32 s7, 0, 0x18000
	v_add_u32_e32 v160, s7, v165
	s_barrier
	ds_read_b128 v[148:151], v160
	ds_read_b128 v[152:155], v160 offset:1024
	ds_read_b128 v[156:159], v160 offset:2048
	ds_read_b128 v[160:163], v160 offset:3072
	s_add_u32 s8, s76, s30
	s_addc_u32 s9, s77, s31
	s_add_u32 s76, s8, s30
	s_mov_b32 m0, s28
	v_lshl_add_u64 v[232:233], s[8:9], 0, v[140:141]
	s_addc_u32 s77, s9, s31
	ds_read_b128 v[196:199], v195 offset:32768
	ds_read_b128 v[200:203], v195 offset:33792
	ds_read_b128 v[204:207], v195 offset:34816
	ds_read_b128 v[208:211], v195 offset:35840
	ds_read_b128 v[212:215], v195 offset:36864
	ds_read_b128 v[216:219], v195 offset:37888
	ds_read_b128 v[220:223], v195 offset:38912
	ds_read_b128 v[224:227], v195 offset:39936
	global_load_lds_dwordx4 v[232:233], off
	v_lshl_add_u64 v[232:233], s[76:77], 0, v[140:141]
	s_mov_b32 m0, s29
	s_nop 0
	global_load_lds_dwordx4 v[232:233], off
	s_waitcnt lgkmcnt(8)
	s_waitcnt vmcnt(10)
	s_barrier
	s_waitcnt lgkmcnt(0)
	s_setprio 1
	s_waitcnt lgkmcnt(0)
	v_mfma_f32_16x16x32_bf16 v[128:131], v[148:151], v[196:199], v[128:131]
	v_mfma_f32_16x16x32_bf16 v[124:127], v[156:159], v[196:199], v[124:127]
	v_mfma_f32_16x16x32_bf16 v[108:111], v[148:151], v[204:207], v[108:111]
	v_mfma_f32_16x16x32_bf16 v[100:103], v[156:159], v[204:207], v[100:103]
	v_mfma_f32_16x16x32_bf16 v[88:91], v[148:151], v[212:215], v[88:91]
	v_mfma_f32_16x16x32_bf16 v[84:87], v[156:159], v[212:215], v[84:87]
	v_mfma_f32_16x16x32_bf16 v[56:59], v[148:151], v[220:223], v[56:59]
	v_mfma_f32_16x16x32_bf16 v[44:47], v[156:159], v[220:223], v[44:47]
	v_mfma_f32_16x16x32_bf16 v[128:131], v[152:155], v[200:203], v[128:131]
	v_mfma_f32_16x16x32_bf16 v[124:127], v[160:163], v[200:203], v[124:127]
	v_mfma_f32_16x16x32_bf16 v[108:111], v[152:155], v[208:211], v[108:111]
	v_mfma_f32_16x16x32_bf16 v[100:103], v[160:163], v[208:211], v[100:103]
	v_mfma_f32_16x16x32_bf16 v[88:91], v[152:155], v[216:219], v[88:91]
	v_mfma_f32_16x16x32_bf16 v[84:87], v[160:163], v[216:219], v[84:87]
	v_mfma_f32_16x16x32_bf16 v[56:59], v[152:155], v[224:227], v[56:59]
	v_mfma_f32_16x16x32_bf16 v[44:47], v[160:163], v[224:227], v[44:47]
	s_setprio 0
	s_barrier
	s_add_i32 s33, 0, 0x1c000
	s_add_i32 s7, s7, s87
	s_add_u32 s2, s2, s94
	v_add_u32_e32 v244, s33, v165
	v_lshl_add_u64 v[248:249], v[248:249], 0, s[16:17]
	s_mov_b32 m0, s7
	s_addc_u32 s3, s3, s95
	ds_read_b128 v[232:235], v244
	ds_read_b128 v[236:239], v244 offset:1024
	ds_read_b128 v[240:243], v244 offset:2048
	ds_read_b128 v[244:247], v244 offset:3072
	global_load_lds_dwordx4 v[248:249], off
	v_lshl_add_u64 v[248:249], s[2:3], 0, v[138:139]
	v_lshl_add_u64 v[248:249], v[248:249], 0, s[16:17]
	s_add_i32 m0, s7, 0x2000
	s_nop 0
	global_load_lds_dwordx4 v[248:249], off
	s_waitcnt vmcnt(10)
	s_barrier
	s_waitcnt lgkmcnt(0)
	s_setprio 1
	s_waitcnt lgkmcnt(0)
	v_mfma_f32_16x16x32_bf16 v[120:123], v[232:235], v[196:199], v[120:123]
	v_mfma_f32_16x16x32_bf16 v[116:119], v[240:243], v[196:199], v[116:119]
	v_mfma_f32_16x16x32_bf16 v[112:115], v[232:235], v[204:207], v[112:115]
	v_mfma_f32_16x16x32_bf16 v[104:107], v[240:243], v[204:207], v[104:107]
	v_mfma_f32_16x16x32_bf16 v[96:99], v[232:235], v[212:215], v[96:99]
	v_mfma_f32_16x16x32_bf16 v[92:95], v[240:243], v[212:215], v[92:95]
	v_mfma_f32_16x16x32_bf16 v[80:83], v[232:235], v[220:223], v[80:83]
	v_mfma_f32_16x16x32_bf16 v[76:79], v[240:243], v[220:223], v[76:79]
	v_mfma_f32_16x16x32_bf16 v[120:123], v[236:239], v[200:203], v[120:123]
	v_mfma_f32_16x16x32_bf16 v[116:119], v[244:247], v[200:203], v[116:119]
	v_mfma_f32_16x16x32_bf16 v[112:115], v[236:239], v[208:211], v[112:115]
	v_mfma_f32_16x16x32_bf16 v[104:107], v[244:247], v[208:211], v[104:107]
	v_mfma_f32_16x16x32_bf16 v[96:99], v[236:239], v[216:219], v[96:99]
	v_mfma_f32_16x16x32_bf16 v[92:95], v[244:247], v[216:219], v[92:95]
	v_mfma_f32_16x16x32_bf16 v[80:83], v[236:239], v[224:227], v[80:83]
	v_mfma_f32_16x16x32_bf16 v[76:79], v[244:247], v[224:227], v[76:79]
	s_setprio 0
	s_add_u32 s8, s8, s96
	s_mov_b32 m0, s40
	v_lshl_add_u64 v[248:249], v[250:251], 0, s[16:17]
	s_addc_u32 s9, s9, s97
	s_barrier
	ds_read_b128 v[196:199], v195 offset:49152
	ds_read_b128 v[200:203], v195 offset:50176
	ds_read_b128 v[204:207], v195 offset:51200
	ds_read_b128 v[208:211], v195 offset:52224
	ds_read_b128 v[212:215], v195 offset:53248
	ds_read_b128 v[216:219], v195 offset:54272
	ds_read_b128 v[220:223], v195 offset:55296
	ds_read_b128 v[224:227], v195 offset:56320
	global_load_lds_dwordx4 v[248:249], off
	v_lshl_add_u64 v[248:249], s[8:9], 0, v[140:141]
	v_lshl_add_u64 v[248:249], v[248:249], 0, s[16:17]
	s_mov_b32 m0, s41
	s_nop 0
	global_load_lds_dwordx4 v[248:249], off
	s_barrier
	s_waitcnt lgkmcnt(0)
	s_setprio 1
	s_waitcnt lgkmcnt(0)
	v_mfma_f32_16x16x32_bf16 v[64:67], v[148:151], v[196:199], v[64:67]
	v_mfma_f32_16x16x32_bf16 v[60:63], v[156:159], v[196:199], v[60:63]
	v_mfma_f32_16x16x32_bf16 v[40:43], v[148:151], v[204:207], v[40:43]
	v_mfma_f32_16x16x32_bf16 v[36:39], v[156:159], v[204:207], v[36:39]
	v_mfma_f32_16x16x32_bf16 v[22:25], v[148:151], v[212:215], v[22:25]
	v_mfma_f32_16x16x32_bf16 v[18:21], v[156:159], v[212:215], v[18:21]
	v_mfma_f32_16x16x32_bf16 v[6:9], v[148:151], v[220:223], v[6:9]
	v_mfma_f32_16x16x32_bf16 v[2:5], v[156:159], v[220:223], v[2:5]
	v_mfma_f32_16x16x32_bf16 v[64:67], v[152:155], v[200:203], v[64:67]
	v_mfma_f32_16x16x32_bf16 v[60:63], v[160:163], v[200:203], v[60:63]
	v_mfma_f32_16x16x32_bf16 v[40:43], v[152:155], v[208:211], v[40:43]
	v_mfma_f32_16x16x32_bf16 v[36:39], v[160:163], v[208:211], v[36:39]
	v_mfma_f32_16x16x32_bf16 v[22:25], v[152:155], v[216:219], v[22:25]
	v_mfma_f32_16x16x32_bf16 v[18:21], v[160:163], v[216:219], v[18:21]
	v_mfma_f32_16x16x32_bf16 v[6:9], v[152:155], v[224:227], v[6:9]
	v_mfma_f32_16x16x32_bf16 v[2:5], v[160:163], v[224:227], v[2:5]
	s_setprio 0
	s_barrier
	s_add_u32 s2, s2, s34
	s_addc_u32 s3, s3, s35
	v_lshl_add_u64 v[148:149], s[2:3], 0, v[138:139]
	s_add_i32 s2, s33, s87
	v_lshl_add_u64 v[148:149], v[148:149], 0, s[16:17]
	s_mov_b32 m0, s2
	s_nop 0
	global_load_lds_dwordx4 v[148:149], off
	v_lshl_add_u64 v[148:149], v[252:253], 0, s[16:17]
	s_add_i32 m0, s2, 0x2000
	s_nop 0
	global_load_lds_dwordx4 v[148:149], off
	s_waitcnt vmcnt(10)
	s_barrier
	s_setprio 1
	v_mfma_f32_16x16x32_bf16 v[72:75], v[232:235], v[196:199], v[72:75]
	v_mfma_f32_16x16x32_bf16 v[68:71], v[240:243], v[196:199], v[68:71]
	v_mfma_f32_16x16x32_bf16 v[52:55], v[232:235], v[204:207], v[52:55]
	v_mfma_f32_16x16x32_bf16 v[48:51], v[240:243], v[204:207], v[48:51]
	v_mfma_f32_16x16x32_bf16 v[32:35], v[232:235], v[212:215], v[32:35]
	v_mfma_f32_16x16x32_bf16 v[28:31], v[240:243], v[212:215], v[28:31]
	v_mfma_f32_16x16x32_bf16 v[14:17], v[232:235], v[220:223], v[14:17]
	v_mfma_f32_16x16x32_bf16 v[10:13], v[240:243], v[220:223], v[10:13]
	v_mfma_f32_16x16x32_bf16 v[72:75], v[236:239], v[200:203], v[72:75]
	v_mfma_f32_16x16x32_bf16 v[68:71], v[244:247], v[200:203], v[68:71]
	v_mfma_f32_16x16x32_bf16 v[52:55], v[236:239], v[208:211], v[52:55]
	v_mfma_f32_16x16x32_bf16 v[48:51], v[244:247], v[208:211], v[48:51]
	v_mfma_f32_16x16x32_bf16 v[32:35], v[236:239], v[216:219], v[32:35]
	v_mfma_f32_16x16x32_bf16 v[28:31], v[244:247], v[216:219], v[28:31]
	v_mfma_f32_16x16x32_bf16 v[14:17], v[236:239], v[224:227], v[14:17]
	v_mfma_f32_16x16x32_bf16 v[10:13], v[244:247], v[224:227], v[10:13]
	s_setprio 0
	s_add_u32 s0, s0, 0x100
	s_addc_u32 s1, s1, 0
	v_lshl_add_u64 v[134:135], v[134:135], 0, s[20:21]
	v_lshl_add_u64 v[132:133], v[132:133], 0, s[20:21]
	s_cmp_ge_u32 s6, s86
	s_mov_b32 s2, s6
	s_barrier
	s_cbranch_scc0 .LBB0_894
	s_and_b64 vcc, exec, s[26:27]
	s_cbranch_vccz .LBB0_1126
	v_add_u32_e32 v148, s81, v166
	v_add_u32_e32 v132, s62, v168
	s_mov_b64 s[2:3], -1
	s_mov_b64 s[0:1], 0
	s_cmp_lt_i32 s63, 4
	s_mov_b64 s[76:77], 0
	s_cbranch_scc1 .LBB0_928
	s_cmp_gt_i32 s63, 6
	s_cbranch_scc0 .LBB0_921
	s_cmp_gt_i32 s63, 7
	s_cbranch_scc0 .LBB0_902
	s_cmp_eq_u32 s63, 8
	s_mov_b64 s[76:77], -1
	s_cbranch_scc0 .LBB0_901
	v_ashrrev_i32_e32 v149, 31, v148
	v_lshl_add_u64 v[134:135], v[148:149], 2, s[42:43]
	global_load_dword v198, v[134:135], off
	global_load_dword v200, v[134:135], off offset:64
	global_load_dword v202, v[134:135], off offset:128
	global_load_dword v204, v[134:135], off offset:192
	global_load_dword v206, v[134:135], off offset:512
	global_load_dword v208, v[134:135], off offset:576
	global_load_dword v210, v[134:135], off offset:640
	global_load_dword v212, v[134:135], off offset:704
	s_mov_b32 s6, 0x800000
	v_add_u32_e32 v152, v132, v167
	v_mov_b64_e32 v[150:151], s[44:45]
	s_movk_i32 s7, 0x2c00
	v_ashrrev_i32_e32 v153, 31, v152
	v_mad_i64_i32 v[160:161], s[2:3], v148, s7, v[150:151]
	v_lshlrev_b64 v[152:153], 1, v[152:153]
	v_lshl_add_u64 v[160:161], v[160:161], 0, v[152:153]
	s_mov_b64 s[2:3], 0x2c000
	v_lshl_add_u64 v[214:215], v[160:161], 0, s[2:3]
	v_lshl_add_u64 v[216:217], v[214:215], 0, s[2:3]
	v_lshl_add_u64 v[218:219], v[216:217], 0, s[2:3]
	s_mov_b64 s[2:3], 0x160000
	v_lshl_add_u64 v[220:221], v[160:161], 0, s[2:3]
	v_lshl_add_u64 v[222:223], v[214:215], 0, s[2:3]
	v_lshl_add_u64 v[224:225], v[216:217], 0, s[2:3]
	v_lshl_add_u64 v[226:227], v[218:219], 0, s[2:3]
	s_mov_b64 s[76:77], 0
	s_waitcnt vmcnt(0)
	v_fmamk_f32 v198, v198, 0x3a800000, v172
	v_fmamk_f32 v200, v200, 0x3a800000, v172
	v_fmamk_f32 v202, v202, 0x3a800000, v172
	v_fmamk_f32 v204, v204, 0x3a800000, v172
	v_fmamk_f32 v206, v206, 0x3a800000, v172
	v_fmamk_f32 v208, v208, 0x3a800000, v172
	v_fmamk_f32 v210, v210, 0x3a800000, v172
	v_fmamk_f32 v212, v212, 0x3a800000, v172
	v_rsq_f32_e32 v198, v198
	v_rsq_f32_e32 v200, v200
	v_rsq_f32_e32 v202, v202
	v_rsq_f32_e32 v204, v204
	v_rsq_f32_e32 v206, v206
	v_rsq_f32_e32 v208, v208
	v_rsq_f32_e32 v210, v210
	v_rsq_f32_e32 v212, v212
	s_nop 0
	v_pk_mul_f32 v[128:129], v[128:129], v[198:199] op_sel_hi:[1,0]
	v_pk_mul_f32 v[130:131], v[130:131], v[198:199] op_sel_hi:[1,0]
	v_pk_mul_f32 v[124:125], v[124:125], v[198:199] op_sel_hi:[1,0]
	v_pk_mul_f32 v[126:127], v[126:127], v[198:199] op_sel_hi:[1,0]
	v_cvt_pk_bf16_f32 v128, v128, v129
	v_cvt_pk_bf16_f32 v129, v130, v131
	v_cvt_pk_bf16_f32 v130, v124, v125
	v_cvt_pk_bf16_f32 v131, v126, v127
	global_store_dwordx4 v[160:161], v[128:131], off
	v_pk_mul_f32 v[120:121], v[120:121], v[198:199] op_sel_hi:[1,0]
	v_pk_mul_f32 v[122:123], v[122:123], v[198:199] op_sel_hi:[1,0]
	v_pk_mul_f32 v[116:117], v[116:117], v[198:199] op_sel_hi:[1,0]
	v_pk_mul_f32 v[118:119], v[118:119], v[198:199] op_sel_hi:[1,0]
	v_cvt_pk_bf16_f32 v120, v120, v121
	v_cvt_pk_bf16_f32 v121, v122, v123
	v_cvt_pk_bf16_f32 v122, v116, v117
	v_cvt_pk_bf16_f32 v123, v118, v119
	global_store_dwordx4 v[160:161], v[120:123], off offset:256
	v_pk_mul_f32 v[108:109], v[108:109], v[200:201] op_sel_hi:[1,0]
	v_pk_mul_f32 v[110:111], v[110:111], v[200:201] op_sel_hi:[1,0]
	v_pk_mul_f32 v[100:101], v[100:101], v[200:201] op_sel_hi:[1,0]
	v_pk_mul_f32 v[102:103], v[102:103], v[200:201] op_sel_hi:[1,0]
	v_cvt_pk_bf16_f32 v108, v108, v109
	v_cvt_pk_bf16_f32 v109, v110, v111
	v_cvt_pk_bf16_f32 v110, v100, v101
	v_cvt_pk_bf16_f32 v111, v102, v103
	global_store_dwordx4 v[214:215], v[108:111], off
	v_pk_mul_f32 v[112:113], v[112:113], v[200:201] op_sel_hi:[1,0]
	v_pk_mul_f32 v[114:115], v[114:115], v[200:201] op_sel_hi:[1,0]
	v_pk_mul_f32 v[104:105], v[104:105], v[200:201] op_sel_hi:[1,0]
	v_pk_mul_f32 v[106:107], v[106:107], v[200:201] op_sel_hi:[1,0]
	v_cvt_pk_bf16_f32 v112, v112, v113
	v_cvt_pk_bf16_f32 v113, v114, v115
	v_cvt_pk_bf16_f32 v114, v104, v105
	v_cvt_pk_bf16_f32 v115, v106, v107
	global_store_dwordx4 v[214:215], v[112:115], off offset:256
	v_pk_mul_f32 v[88:89], v[88:89], v[202:203] op_sel_hi:[1,0]
	v_pk_mul_f32 v[90:91], v[90:91], v[202:203] op_sel_hi:[1,0]
	v_pk_mul_f32 v[84:85], v[84:85], v[202:203] op_sel_hi:[1,0]
	v_pk_mul_f32 v[86:87], v[86:87], v[202:203] op_sel_hi:[1,0]
	v_cvt_pk_bf16_f32 v88, v88, v89
	v_cvt_pk_bf16_f32 v89, v90, v91
	v_cvt_pk_bf16_f32 v90, v84, v85
	v_cvt_pk_bf16_f32 v91, v86, v87
	global_store_dwordx4 v[216:217], v[88:91], off
	v_pk_mul_f32 v[96:97], v[96:97], v[202:203] op_sel_hi:[1,0]
	v_pk_mul_f32 v[98:99], v[98:99], v[202:203] op_sel_hi:[1,0]
	v_pk_mul_f32 v[92:93], v[92:93], v[202:203] op_sel_hi:[1,0]
	v_pk_mul_f32 v[94:95], v[94:95], v[202:203] op_sel_hi:[1,0]
	v_cvt_pk_bf16_f32 v96, v96, v97
	v_cvt_pk_bf16_f32 v97, v98, v99
	v_cvt_pk_bf16_f32 v98, v92, v93
	v_cvt_pk_bf16_f32 v99, v94, v95
	global_store_dwordx4 v[216:217], v[96:99], off offset:256
	v_pk_mul_f32 v[56:57], v[56:57], v[204:205] op_sel_hi:[1,0]
	v_pk_mul_f32 v[58:59], v[58:59], v[204:205] op_sel_hi:[1,0]
	v_pk_mul_f32 v[44:45], v[44:45], v[204:205] op_sel_hi:[1,0]
	v_pk_mul_f32 v[46:47], v[46:47], v[204:205] op_sel_hi:[1,0]
	v_cvt_pk_bf16_f32 v56, v56, v57
	v_cvt_pk_bf16_f32 v57, v58, v59
	v_cvt_pk_bf16_f32 v58, v44, v45
	v_cvt_pk_bf16_f32 v59, v46, v47
	global_store_dwordx4 v[218:219], v[56:59], off
	v_pk_mul_f32 v[80:81], v[80:81], v[204:205] op_sel_hi:[1,0]
	v_pk_mul_f32 v[82:83], v[82:83], v[204:205] op_sel_hi:[1,0]
	v_pk_mul_f32 v[76:77], v[76:77], v[204:205] op_sel_hi:[1,0]
	v_pk_mul_f32 v[78:79], v[78:79], v[204:205] op_sel_hi:[1,0]
	v_cvt_pk_bf16_f32 v80, v80, v81
	v_cvt_pk_bf16_f32 v81, v82, v83
	v_cvt_pk_bf16_f32 v82, v76, v77
	v_cvt_pk_bf16_f32 v83, v78, v79
	global_store_dwordx4 v[218:219], v[80:83], off offset:256
	v_pk_mul_f32 v[64:65], v[64:65], v[206:207] op_sel_hi:[1,0]
	v_pk_mul_f32 v[66:67], v[66:67], v[206:207] op_sel_hi:[1,0]
	v_pk_mul_f32 v[60:61], v[60:61], v[206:207] op_sel_hi:[1,0]
	v_pk_mul_f32 v[62:63], v[62:63], v[206:207] op_sel_hi:[1,0]
	v_cvt_pk_bf16_f32 v64, v64, v65
	v_cvt_pk_bf16_f32 v65, v66, v67
	v_cvt_pk_bf16_f32 v66, v60, v61
	v_cvt_pk_bf16_f32 v67, v62, v63
	global_store_dwordx4 v[220:221], v[64:67], off
	v_pk_mul_f32 v[72:73], v[72:73], v[206:207] op_sel_hi:[1,0]
	v_pk_mul_f32 v[74:75], v[74:75], v[206:207] op_sel_hi:[1,0]
	v_pk_mul_f32 v[68:69], v[68:69], v[206:207] op_sel_hi:[1,0]
	v_pk_mul_f32 v[70:71], v[70:71], v[206:207] op_sel_hi:[1,0]
	v_cvt_pk_bf16_f32 v72, v72, v73
	v_cvt_pk_bf16_f32 v73, v74, v75
	v_cvt_pk_bf16_f32 v74, v68, v69
	v_cvt_pk_bf16_f32 v75, v70, v71
	global_store_dwordx4 v[220:221], v[72:75], off offset:256
	v_pk_mul_f32 v[40:41], v[40:41], v[208:209] op_sel_hi:[1,0]
	v_pk_mul_f32 v[42:43], v[42:43], v[208:209] op_sel_hi:[1,0]
	v_pk_mul_f32 v[36:37], v[36:37], v[208:209] op_sel_hi:[1,0]
	v_pk_mul_f32 v[38:39], v[38:39], v[208:209] op_sel_hi:[1,0]
	v_cvt_pk_bf16_f32 v40, v40, v41
	v_cvt_pk_bf16_f32 v41, v42, v43
	v_cvt_pk_bf16_f32 v42, v36, v37
	v_cvt_pk_bf16_f32 v43, v38, v39
	global_store_dwordx4 v[222:223], v[40:43], off
	v_pk_mul_f32 v[52:53], v[52:53], v[208:209] op_sel_hi:[1,0]
	v_pk_mul_f32 v[54:55], v[54:55], v[208:209] op_sel_hi:[1,0]
	v_pk_mul_f32 v[48:49], v[48:49], v[208:209] op_sel_hi:[1,0]
	v_pk_mul_f32 v[50:51], v[50:51], v[208:209] op_sel_hi:[1,0]
	v_cvt_pk_bf16_f32 v52, v52, v53
	v_cvt_pk_bf16_f32 v53, v54, v55
	v_cvt_pk_bf16_f32 v54, v48, v49
	v_cvt_pk_bf16_f32 v55, v50, v51
	global_store_dwordx4 v[222:223], v[52:55], off offset:256
	v_pk_mul_f32 v[22:23], v[22:23], v[210:211] op_sel_hi:[1,0]
	v_pk_mul_f32 v[24:25], v[24:25], v[210:211] op_sel_hi:[1,0]
	v_pk_mul_f32 v[18:19], v[18:19], v[210:211] op_sel_hi:[1,0]
	v_pk_mul_f32 v[20:21], v[20:21], v[210:211] op_sel_hi:[1,0]
	v_cvt_pk_bf16_f32 v22, v22, v23
	v_cvt_pk_bf16_f32 v23, v24, v25
	v_cvt_pk_bf16_f32 v24, v18, v19
	v_cvt_pk_bf16_f32 v25, v20, v21
	global_store_dwordx4 v[224:225], v[22:25], off
	v_pk_mul_f32 v[32:33], v[32:33], v[210:211] op_sel_hi:[1,0]
	v_pk_mul_f32 v[34:35], v[34:35], v[210:211] op_sel_hi:[1,0]
	v_pk_mul_f32 v[28:29], v[28:29], v[210:211] op_sel_hi:[1,0]
	v_pk_mul_f32 v[30:31], v[30:31], v[210:211] op_sel_hi:[1,0]
	v_cvt_pk_bf16_f32 v32, v32, v33
	v_cvt_pk_bf16_f32 v33, v34, v35
	v_cvt_pk_bf16_f32 v34, v28, v29
	v_cvt_pk_bf16_f32 v35, v30, v31
	global_store_dwordx4 v[224:225], v[32:35], off offset:256
	v_pk_mul_f32 v[6:7], v[6:7], v[212:213] op_sel_hi:[1,0]
	v_pk_mul_f32 v[8:9], v[8:9], v[212:213] op_sel_hi:[1,0]
	v_pk_mul_f32 v[2:3], v[2:3], v[212:213] op_sel_hi:[1,0]
	v_pk_mul_f32 v[4:5], v[4:5], v[212:213] op_sel_hi:[1,0]
	v_cvt_pk_bf16_f32 v6, v6, v7
	v_cvt_pk_bf16_f32 v7, v8, v9
	v_cvt_pk_bf16_f32 v8, v2, v3
	v_cvt_pk_bf16_f32 v9, v4, v5
	global_store_dwordx4 v[226:227], v[6:9], off
	v_pk_mul_f32 v[14:15], v[14:15], v[212:213] op_sel_hi:[1,0]
	v_pk_mul_f32 v[16:17], v[16:17], v[212:213] op_sel_hi:[1,0]
	v_pk_mul_f32 v[10:11], v[10:11], v[212:213] op_sel_hi:[1,0]
	v_pk_mul_f32 v[12:13], v[12:13], v[212:213] op_sel_hi:[1,0]
	v_cvt_pk_bf16_f32 v14, v14, v15
	v_cvt_pk_bf16_f32 v15, v16, v17
	v_cvt_pk_bf16_f32 v16, v10, v11
	v_cvt_pk_bf16_f32 v17, v12, v13
	global_store_dwordx4 v[226:227], v[14:17], off offset:256
